# barrier leader releases followers (XGEN add) before its own buffer_inv acquire, at the 3 chip-wide barriers
# speedup vs baseline: 1.0001x; 1.0001x over previous
; DI unsigned xb_ld(unsigned* p) { return __hip_atomic_load(p, __ATOMIC_RELAXED, __HIP_MEMORY_SCOPE_AGENT); }
; DI unsigned xb_add(unsigned* p, unsigned v) { return __hip_atomic_fetch_add(p, v, __ATOMIC_RELAXED, __HIP_MEMORY_SCOPE_AGENT); }
; #define XB_SPIN(cond, bar) do { unsigned _sp = 0; while (cond) { __builtin_amdgcn_s_sleep(1); \
;     if ((++_sp & 255u) == 0u) { if (xb_ld(&(bar)[XB_TMO])) break; if (_sp > XB_SPIN_CAP) { atomicAdd(&(bar)[XB_TMO], 1u); break; } } } } while (0)
; DI void xcd_barrier(const XcdBarrier& b) {
;     ...
;       __builtin_amdgcn_fence(__ATOMIC_RELEASE, "agent");
;       asm volatile("s_waitcnt vmcnt(0)" ::: "memory");
;       const unsigned og = xb_add(&bar[XB_TOP], 1u);
;       const unsigned tg = og / nx;
;       if (og + 1u == (tg + 1u) * nx) xb_add(&bar[XB_TOPGEN], 1u);
;       else XB_SPIN(xb_ld(&bar[XB_TOPGEN]) == tg, bar);
;       __builtin_amdgcn_fence(__ATOMIC_ACQUIRE, "agent");
;       xb_add(&bar[XB_XGEN(b.x)], 1u);
;       asm volatile("s_waitcnt vmcnt(0)" ::: "memory");
; __global__ void __launch_bounds__(256, 2) k_mega(Params p) {
;     ...
;   xcd_barrier(xb);
;   Sched sc; sc.nloc = (int)xb_words.x; sc.nx = (int)xb_words.y; sc.rank = (int)xb_words.z; sc.xi = (int)xb_words.w;
;   if (__builtin_amdgcn_readfirstlane(sc.rank) * 2 >= __builtin_amdgcn_readfirstlane(sc.nloc)) __builtin_amdgcn_s_setprio(1);
.LBB0_151:
	s_or_b64 exec, exec, s[4:5]
	s_mov_b64 s[4:5], exec
	v_mbcnt_lo_u32_b32 v0, s4, 0
	v_mbcnt_hi_u32_b32 v0, s5, v0
	v_cmp_eq_u32_e32 vcc, 0, v0
	s_and_saveexec_b64 s[6:7], vcc
	s_cbranch_execz .LBB0_153
	s_bcnt1_i32_b64 s4, s[4:5]
	v_mov_b32_e32 v0, 0x2000
	v_mov_b32_e32 v1, s4
	global_atomic_add v0, v1, s[2:3] offset:1024
.LBB0_153:
	s_or_b64 exec, exec, s[6:7]
	s_waitcnt vmcnt(0)
	buffer_inv sc1
	s_waitcnt vmcnt(0)
.LBB0_154:
	v_writelane_b32 v255, s44, 4
	s_or_b64 exec, exec, s[0:1]
	s_waitcnt lgkmcnt(0)
	v_mov_b32_e32 v0, 0x12400
	s_barrier
	ds_read_b128 v[0:3], v0
	s_waitcnt lgkmcnt(0)
	v_readfirstlane_b32 s75, v2
	v_readfirstlane_b32 s33, v0
	s_lshl_b32 s0, s75, 1
	v_readfirstlane_b32 s74, v1
	s_cmp_lt_i32 s0, s33
	v_readfirstlane_b32 s76, v3
	s_cbranch_scc1 .LBB0_156
	s_setprio 1

; DI unsigned xb_ld(unsigned* p) { return __hip_atomic_load(p, __ATOMIC_RELAXED, __HIP_MEMORY_SCOPE_AGENT); }
; DI unsigned xb_add(unsigned* p, unsigned v) { return __hip_atomic_fetch_add(p, v, __ATOMIC_RELAXED, __HIP_MEMORY_SCOPE_AGENT); }
; #define XB_SPIN(cond, bar) do { unsigned _sp = 0; while (cond) { __builtin_amdgcn_s_sleep(1); \
;     if ((++_sp & 255u) == 0u) { if (xb_ld(&(bar)[XB_TMO])) break; if (_sp > XB_SPIN_CAP) { atomicAdd(&(bar)[XB_TMO], 1u); break; } } } } while (0)
; DI void xcd_barrier(const XcdBarrier& b) {
;     ...
;       __builtin_amdgcn_fence(__ATOMIC_ACQUIRE, "agent");
;       xb_add(&bar[XB_XGEN(b.x)], 1u);
;       asm volatile("s_waitcnt vmcnt(0)" ::: "memory");
;     } else {
;       XB_SPIN(xb_ld(&bar[XB_XGEN(b.x)]) == gen, bar);
;       __builtin_amdgcn_fence(__ATOMIC_ACQUIRE, "agent");
;       asm volatile("s_waitcnt vmcnt(0)" ::: "memory");
; DI void phase4(const Params& p, char* smem, const Sched sc) {
;     ...
;   for (int i = 0; i < 96; ++i) { gq = fmaxf(gq, fabsf(p.qhn[i])); gk = fmaxf(gk, fabsf(p.khn[i])); }
.LBB0_416:
	s_or_b64 exec, exec, s[6:7]
	s_waitcnt vmcnt(0)
	buffer_inv sc1
	s_waitcnt vmcnt(0)
.LBB0_417:
	s_or_b64 exec, exec, s[0:1]
	s_load_dwordx4 s[8:11], s[68:69], 0x58
	s_mov_b64 s[0:1], 0
	s_waitcnt lgkmcnt(0)
	v_mov_b32_e32 v0, 0
	v_mov_b32_e32 v1, 0
	v_mov_b32_e32 v2, 0
	s_barrier

; DI unsigned xb_ld(unsigned* p) { return __hip_atomic_load(p, __ATOMIC_RELAXED, __HIP_MEMORY_SCOPE_AGENT); }
; DI unsigned xb_add(unsigned* p, unsigned v) { return __hip_atomic_fetch_add(p, v, __ATOMIC_RELAXED, __HIP_MEMORY_SCOPE_AGENT); }
; #define XB_SPIN(cond, bar) do { unsigned _sp = 0; while (cond) { __builtin_amdgcn_s_sleep(1); \
;     if ((++_sp & 255u) == 0u) { if (xb_ld(&(bar)[XB_TMO])) break; if (_sp > XB_SPIN_CAP) { atomicAdd(&(bar)[XB_TMO], 1u); break; } } } } while (0)
; DI void xcd_barrier(const XcdBarrier& b) {
;     ...
;       __builtin_amdgcn_fence(__ATOMIC_ACQUIRE, "agent");
;       xb_add(&bar[XB_XGEN(b.x)], 1u);
;       asm volatile("s_waitcnt vmcnt(0)" ::: "memory");
;     } else {
;       XB_SPIN(xb_ld(&bar[XB_XGEN(b.x)]) == gen, bar);
;       __builtin_amdgcn_fence(__ATOMIC_ACQUIRE, "agent");
;       asm volatile("s_waitcnt vmcnt(0)" ::: "memory");
; DI void phase5(const Params& p, char* smem, const Sched sc) {
;   const int tid = threadIdx.x, lane = tid & 63, wave = tid >> 6, r = lane & 31, h = lane >> 5, wr = wave >> 1, wc = wave & 1;
;   constexpr int CST = 132;
;   float* ct = (float*)smem;
;   for (int v = sc.xi; v < 8; v += sc.nx)
;   for (int l = sc.rank; l < 16 * 8; l += sc.nloc) {
;     const int g8 = l >> 6, rem = l & 63, nt = rem >> 3, mt = 16 * v + 8 * g8 + (rem & 7), m0 = mt * 128, n0 = nt * 128;
;     f32x16 acc[2][2];
;     gemm_tile<128, 128, 2, 2, false, true>(p.WoutT + (size_t)n0 * DM, DM, p.Mixed + (size_t)m0 * DM, DM, DM, smem, acc, nullptr);
;     const int b = m0 >> 13;
; #pragma unroll
;     for (int mi = 0; mi < 2; ++mi)
; #pragma unroll
;       for (int ni = 0; ni < 2; ++ni)
; #pragma unroll
;         for (int g = 0; g < 4; ++g) {
;           const f32x4 vv = {acc[mi][ni][4 * g], acc[mi][ni][4 * g + 1], acc[mi][ni][4 * g + 2], acc[mi][ni][4 * g + 3]};
;           *(f32x4*)(ct + (wc * 64 + ni * 32 + r) * CST + wr * 64 + mi * 32 + 8 * g + 4 * h) = vv;
;         }
;     __syncthreads();
;     const int c4 = (tid & 31) * 4, row0 = tid >> 5;
;     const f32x4 gt = *(const f32x4*)(p.ada + b * 3072 + 2048 + n0 + c4);
.LBB0_523:
	s_or_b64 exec, exec, s[6:7]
	s_waitcnt vmcnt(0)
	buffer_inv sc1
	s_waitcnt vmcnt(0)
.LBB0_524:
	s_or_b64 exec, exec, s[0:1]
	v_readlane_b32 s0, v255, 5
	v_readlane_b32 s1, v255, 6
	s_and_b64 vcc, exec, s[0:1]
	s_waitcnt lgkmcnt(0)
	s_barrier
	s_cbranch_vccnz .LBB0_530
	v_and_b32_e32 v1, 0x1c0, v213
	v_and_b32_e32 v0, 0x70, v214
	s_movk_i32 s2, 0x90
	v_and_or_b32 v2, v241, 31, v1
	v_and_b32_e32 v3, 0x5f, v241
	v_and_b32_e32 v4, 16, v213
	s_waitcnt vmcnt(2)
	v_mad_u32_u24 v120, v232, s2, v0
	v_mad_u32_u24 v121, v2, s2, v4
	v_mad_u32_u24 v122, v3, s2, v4
	s_load_dwordx2 s[2:3], s[68:69], 0xb0
	s_load_dwordx2 s[8:9], s[68:69], 0x110
	v_lshlrev_b32_e32 v96, 11, v232
	v_mov_b32_e32 v97, 0
	v_lshl_or_b32 v8, v1, 2, v4
	s_waitcnt lgkmcnt(0)
	v_lshl_add_u64 v[6:7], s[2:3], 0, v[96:97]
	s_load_dwordx4 s[4:7], s[68:69], 0x70
	s_load_dwordx2 s[2:3], s[68:69], 0x0
	v_lshlrev_b32_e32 v1, 2, v241
	s_cmpk_lt_i32 s75, 0x80
	v_and_b32_e32 v2, 0x7c, v1
	v_mov_b32_e32 v1, v97
	s_cselect_b64 s[0:1], -1, 0
	s_waitcnt vmcnt(1)
	v_lshrrev_b32_e32 v124, 5, v241
	v_lshl_add_u64 v[98:99], v[6:7], 0, v[0:1]
	v_lshl_add_u64 v[6:7], s[8:9], 0, v[96:97]
	v_lshlrev_b32_e32 v4, 2, v2
	v_mul_u32_u24_e32 v3, 0x210, v3
	v_mul_u32_u24_e32 v9, 0x210, v124
	v_lshl_add_u64 v[100:101], v[6:7], 0, v[0:1]
	v_mov_b32_e32 v5, v97
	v_cndmask_b32_e64 v0, 0, 1, s[0:1]
	v_add_u32_e32 v123, 0xd800, v120
	v_add_u32_e32 v125, 8, v124
	v_add_u32_e32 v126, 16, v124
	v_add_u32_e32 v127, 24, v124
	s_waitcnt vmcnt(0)
	v_or_b32_e32 v128, 32, v124
	v_add_u32_e32 v129, 40, v124
	v_add_u32_e32 v130, 48, v124
	v_add_u32_e32 v131, 56, v124
	v_or_b32_e32 v132, 64, v124
	v_add_u32_e32 v133, 0x48, v124
	v_add_u32_e32 v134, 0x50, v124
	v_add_u32_e32 v135, 0x58, v124
	v_or_b32_e32 v136, 0x60, v124
	v_add_u32_e32 v137, 0x68, v124
	v_add_u32_e32 v138, 0x70, v124
	v_add_u32_e32 v139, 0x78, v124
	s_waitcnt lgkmcnt(0)
	v_lshl_add_u64 v[102:103], s[2:3], 0, v[4:5]
	s_lshl_b32 s10, s75, 4
	s_lshl_b32 s11, s33, 4
	v_cmp_ne_u32_e64 s[0:1], 1, v0
	s_mov_b32 s3, 0
	s_mov_b32 s12, 0x10000
	s_mov_b32 s13, 0x20000
	s_mov_b32 s14, 0x30000
	v_add_u32_e32 v140, v8, v3
	v_lshlrev_b32_e32 v96, 2, v2
	s_movk_i32 s15, 0x2000
	s_mov_b32 s16, 0x8000
	s_mov_b32 s17, 0x18000
	s_mov_b32 s18, 0x28000
	s_mov_b32 s19, 0x38000
	v_add_u32_e32 v141, v4, v9
	s_mov_b32 s20, 0x48000
	s_mov_b32 s21, 0x50000
	s_mov_b32 s22, 0x58000
	s_branch .LBB0_527
